# v17 = v13 + attention unit prologue issues bound/rope-table/Q loads before the K0/V0/K1 DMAs
# baseline (speedup 1.0000x reference)
.LBB0_554:
	s_mul_i32 s9, s56, 0xc00000
	v_readlane_b32 s52, v246, 43
	s_mul_hi_i32 s8, s56, 0xc00000
	s_add_u32 s52, s52, s9
	v_readlane_b32 s9, v246, 44
	s_addc_u32 s60, s9, s8
	s_lshl_b32 s8, s1, 6
	s_ashr_i32 s9, s8, 31
	s_lshl_b64 s[58:59], s[8:9], 1
	s_add_u32 s8, s52, s58
	s_addc_u32 s9, s60, s59
	s_add_u32 s60, s64, 0x24000
	s_addc_u32 s61, s65, 0
	s_cmp_lg_u32 0, -1
	s_cselect_b32 s1, 0, 0
	s_add_i32 s1, s1, s73
	s_addk_i32 s1, 0x3000
	s_add_u32 s66, s46, 0x1000
	s_addc_u32 s67, s47, 0
	s_add_i32 s1, s76, 0x3000
.LBB0_556:
	s_lshl_b64 s[60:61], s[56:57], 18
	v_readlane_b32 s1, v246, 39
	s_add_u32 s1, s1, s44
	v_readlane_b32 s44, v246, 40
	s_addc_u32 s44, s44, s45
	s_add_u32 s1, s1, s48
	s_addc_u32 s48, s44, s49
	s_lshl_b64 s[44:45], s[60:61], 2
	v_readlane_b32 s49, v246, 51
	s_add_u32 s44, s49, s44
	v_readlane_b32 s49, v246, 52
	s_addc_u32 s45, s49, s45
	s_lshl_b32 s81, s62, 8
	s_add_i32 s52, s81, s71
	v_or_b32_e32 v0, s52, v170
	v_mov_b32_e32 v1, v153
	v_lshlrev_b64 v[0:1], 7, v[0:1]
	v_lshl_add_u64 v[0:1], s[44:45], 0, v[0:1]
	v_lshl_add_u64 v[12:13], v[146:147], 2, v[0:1]
	s_mul_i32 s44, s52, 0x900
	s_mov_b32 s98, s0
	s_ashr_i32 s99, s0, 31
	s_lshl_b64 s[98:99], s[98:99], 9
	s_lshl_b32 s100, s56, 7
	s_ashr_i32 s101, s100, 31
	v_lshl_add_u64 v[250:251], v[162:163], 0, s[98:99]
	v_lshl_add_u64 v[252:253], s[100:101], 2, v[164:165]
	global_load_dword v247, v[250:251], off
	global_load_dword v248, v[250:251], off offset:256
	global_load_dword v249, v[252:253], off
	global_load_dword v254, v[252:253], off offset:256
	global_load_dwordx4 v[0:3], v[12:13], off
	global_load_dwordx4 v[4:7], v[12:13], off offset:16
	s_mul_hi_u32 s45, s52, 0x900
	global_load_dwordx4 v[8:11], v[12:13], off offset:48
	s_nop 0
	global_load_dwordx4 v[12:15], v[12:13], off offset:32
	s_add_u32 s44, s1, s44
	s_addc_u32 s45, s48, s45
	v_lshl_add_u64 v[16:17], s[44:45], 0, v[152:153]
	v_lshl_add_u64 v[24:25], v[150:151], 1, v[16:17]
	global_load_dwordx4 v[16:19], v[24:25], off offset:128
	global_load_dwordx4 v[20:23], v[24:25], off offset:160
	global_load_dwordx4 v[116:119], v[24:25], off
	global_load_dwordx4 v[112:115], v[24:25], off offset:32
	global_load_dwordx4 v[104:107], v[24:25], off offset:64
	global_load_dwordx4 v[96:99], v[24:25], off offset:96
	s_mov_b32 m0, s55
	s_nop 0
	global_load_lds_dwordx4 v183, s[64:65]
	s_and_saveexec_b64 s[100:101], s[2:3]
	s_mov_b32 m0, s76
	s_nop 0
	global_load_lds_dwordx4 v184, s[46:47]
	s_or_b64 exec, exec, s[100:101]
	s_mov_b32 m0, s33
	s_nop 0
	global_load_lds_dwordx4 v185, s[8:9]
	s_add_u32 s98, s64, 0x24000
	s_addc_u32 s99, s65, 0
	s_add_i32 m0, s73, 0x3000
	s_nop 0
	global_load_lds_dwordx4 v183, s[98:99]
	s_and_saveexec_b64 s[100:101], s[2:3]
	s_add_u32 s98, s46, 0x1000
	s_addc_u32 s99, s47, 0
	s_add_i32 m0, s76, 0x3000
	s_nop 0
	global_load_lds_dwordx4 v184, s[98:99]
	s_or_b64 exec, exec, s[100:101]
	v_readlane_b32 s44, v246, 58
	v_readlane_b32 s45, v246, 59
	s_andn2_b64 vcc, exec, s[44:45]
	s_waitcnt vmcnt(14)
	v_mov_b32_e32 v24, v0
	v_mov_b32_e32 v25, v2
	v_mov_b32_e32 v2, v1
	s_waitcnt vmcnt(13)
	v_mov_b32_e32 v0, v4
	v_mov_b32_e32 v1, v6
	v_mov_b32_e32 v6, v5
	s_waitcnt vmcnt(11)
	v_mov_b32_e32 v4, v12
	v_mov_b32_e32 v5, v14
	v_mov_b32_e32 v14, v13
	v_mov_b32_e32 v12, v8
	v_mov_b32_e32 v13, v10
	v_mov_b32_e32 v10, v9
	s_waitcnt vmcnt(10)
	v_and_b32_e32 v9, 0xffff0000, v16
	v_lshlrev_b32_e32 v8, 16, v16
	s_waitcnt vmcnt(9)
	v_and_b32_e32 v27, 0xffff0000, v20
	v_lshlrev_b32_e32 v26, 16, v20
	v_and_b32_e32 v29, 0xffff0000, v17
	v_lshlrev_b32_e32 v28, 16, v17
	v_and_b32_e32 v17, 0xffff0000, v21
	v_lshlrev_b32_e32 v16, 16, v21
	v_and_b32_e32 v21, 0xffff0000, v18
	v_lshlrev_b32_e32 v20, 16, v18
	v_and_b32_e32 v31, 0xffff0000, v22
	v_lshlrev_b32_e32 v30, 16, v22
	v_and_b32_e32 v33, 0xffff0000, v19
	v_lshlrev_b32_e32 v32, 16, v19
	v_and_b32_e32 v19, 0xffff0000, v23
	v_lshlrev_b32_e32 v18, 16, v23
	v_pk_mul_f32 v[22:23], v[2:3], v[26:27]
	v_pk_mul_f32 v[26:27], v[24:25], v[26:27]
	v_pk_mul_f32 v[34:35], v[6:7], v[16:17]
	v_pk_mul_f32 v[16:17], v[0:1], v[16:17]
	v_pk_mul_f32 v[36:37], v[14:15], v[30:31]
	v_pk_mul_f32 v[30:31], v[4:5], v[30:31]
	v_pk_mul_f32 v[38:39], v[10:11], v[18:19]
	v_pk_mul_f32 v[18:19], v[12:13], v[18:19]
	v_pk_fma_f32 v[22:23], v[24:25], v[8:9], v[22:23] neg_lo:[0,0,1] neg_hi:[0,0,1]
	v_pk_fma_f32 v[2:3], v[2:3], v[8:9], v[26:27]
	v_pk_fma_f32 v[0:1], v[0:1], v[28:29], v[34:35] neg_lo:[0,0,1] neg_hi:[0,0,1]
	v_pk_fma_f32 v[6:7], v[6:7], v[28:29], v[16:17]
	v_pk_fma_f32 v[4:5], v[4:5], v[20:21], v[36:37] neg_lo:[0,0,1] neg_hi:[0,0,1]
	v_pk_fma_f32 v[8:9], v[14:15], v[20:21], v[30:31]
	v_pk_fma_f32 v[12:13], v[12:13], v[32:33], v[38:39] neg_lo:[0,0,1] neg_hi:[0,0,1]
	v_pk_fma_f32 v[10:11], v[10:11], v[32:33], v[18:19]
	v_cvt_pk_bf16_f32 v108, v22, v23
	v_cvt_pk_bf16_f32 v109, v0, v1
	v_cvt_pk_bf16_f32 v110, v4, v5
	v_cvt_pk_bf16_f32 v111, v12, v13
	v_cvt_pk_bf16_f32 v100, v2, v3
	v_cvt_pk_bf16_f32 v101, v6, v7
	v_cvt_pk_bf16_f32 v102, v8, v9
	v_cvt_pk_bf16_f32 v103, v10, v11
	s_cbranch_vccnz .LBB0_558
	s_waitcnt vmcnt(8)
	v_lshlrev_b32_e32 v0, 16, v116
	v_fma_f32 v0, v0, v0, 0
	v_and_b32_e32 v1, 0xffff0000, v116
	v_fmac_f32_e32 v0, v1, v1
	v_lshlrev_b32_e32 v1, 16, v117
	v_fmac_f32_e32 v0, v1, v1
	v_and_b32_e32 v1, 0xffff0000, v117
	v_fmac_f32_e32 v0, v1, v1
	v_lshlrev_b32_e32 v1, 16, v118
	v_fmac_f32_e32 v0, v1, v1
	v_and_b32_e32 v1, 0xffff0000, v118
	v_fmac_f32_e32 v0, v1, v1
	v_lshlrev_b32_e32 v1, 16, v119
	v_fmac_f32_e32 v0, v1, v1
	v_and_b32_e32 v1, 0xffff0000, v119
	v_fmac_f32_e32 v0, v1, v1
	s_waitcnt vmcnt(7)
	v_lshlrev_b32_e32 v1, 16, v112
	v_fmac_f32_e32 v0, v1, v1
	v_and_b32_e32 v1, 0xffff0000, v112
	v_fmac_f32_e32 v0, v1, v1
	v_lshlrev_b32_e32 v1, 16, v113
	v_fmac_f32_e32 v0, v1, v1
	v_and_b32_e32 v1, 0xffff0000, v113
	v_fmac_f32_e32 v0, v1, v1
	v_lshlrev_b32_e32 v1, 16, v114
	v_fmac_f32_e32 v0, v1, v1
	v_and_b32_e32 v1, 0xffff0000, v114
	v_fmac_f32_e32 v0, v1, v1
	v_lshlrev_b32_e32 v1, 16, v115
	v_fmac_f32_e32 v0, v1, v1
	v_and_b32_e32 v1, 0xffff0000, v115
	v_fmac_f32_e32 v0, v1, v1
	s_waitcnt vmcnt(6)
	v_lshlrev_b32_e32 v1, 16, v104
	v_fmac_f32_e32 v0, v1, v1
	v_and_b32_e32 v1, 0xffff0000, v104
	v_fmac_f32_e32 v0, v1, v1
	v_lshlrev_b32_e32 v1, 16, v105
	v_fmac_f32_e32 v0, v1, v1
	v_and_b32_e32 v1, 0xffff0000, v105
	v_fmac_f32_e32 v0, v1, v1
	v_lshlrev_b32_e32 v1, 16, v106
	v_fmac_f32_e32 v0, v1, v1
	v_and_b32_e32 v1, 0xffff0000, v106
	v_fmac_f32_e32 v0, v1, v1
	v_lshlrev_b32_e32 v1, 16, v107
	v_fmac_f32_e32 v0, v1, v1
	v_and_b32_e32 v1, 0xffff0000, v107
	v_fmac_f32_e32 v0, v1, v1
	s_waitcnt vmcnt(5)
	v_lshlrev_b32_e32 v1, 16, v96
	v_fmac_f32_e32 v0, v1, v1
	v_and_b32_e32 v1, 0xffff0000, v96
	v_fmac_f32_e32 v0, v1, v1
	v_lshlrev_b32_e32 v1, 16, v97
	v_fmac_f32_e32 v0, v1, v1
	v_and_b32_e32 v1, 0xffff0000, v97
	v_fmac_f32_e32 v0, v1, v1
	v_lshlrev_b32_e32 v1, 16, v98
	v_fmac_f32_e32 v0, v1, v1
	v_and_b32_e32 v1, 0xffff0000, v98
	v_fmac_f32_e32 v0, v1, v1
	v_lshlrev_b32_e32 v1, 16, v99
	v_fmac_f32_e32 v0, v1, v1
	v_and_b32_e32 v1, 0xffff0000, v99
	v_fmac_f32_e32 v0, v1, v1
	v_lshlrev_b32_e32 v1, 16, v108
	v_fmac_f32_e32 v0, v1, v1
	v_and_b32_e32 v1, 0xffff0000, v108
	v_fmac_f32_e32 v0, v1, v1
	v_lshlrev_b32_e32 v1, 16, v109
	v_fmac_f32_e32 v0, v1, v1
	v_and_b32_e32 v1, 0xffff0000, v109
	v_fmac_f32_e32 v0, v1, v1
	v_lshlrev_b32_e32 v1, 16, v110
	v_fmac_f32_e32 v0, v1, v1
	v_and_b32_e32 v1, 0xffff0000, v110
	v_fmac_f32_e32 v0, v1, v1
	v_lshlrev_b32_e32 v1, 16, v111
	v_fmac_f32_e32 v0, v1, v1
	v_and_b32_e32 v1, 0xffff0000, v111
	v_fmac_f32_e32 v0, v1, v1
	v_lshlrev_b32_e32 v1, 16, v100
	v_fmac_f32_e32 v0, v1, v1
	v_and_b32_e32 v1, 0xffff0000, v100
	v_fmac_f32_e32 v0, v1, v1
	v_lshlrev_b32_e32 v1, 16, v101
	v_fmac_f32_e32 v0, v1, v1
	v_and_b32_e32 v1, 0xffff0000, v101
	v_fmac_f32_e32 v0, v1, v1
	v_lshlrev_b32_e32 v1, 16, v102
	v_fmac_f32_e32 v0, v1, v1
	v_and_b32_e32 v1, 0xffff0000, v102
	v_fmac_f32_e32 v0, v1, v1
	v_lshlrev_b32_e32 v1, 16, v103
	v_fmac_f32_e32 v0, v1, v1
	v_and_b32_e32 v1, 0xffff0000, v103
	s_ashr_i32 s1, s0, 31
	v_fmac_f32_e32 v0, v1, v1
	s_lshl_b64 s[0:1], s[0:1], 9
	s_lshl_b32 s44, s56, 7
	v_mov_b32_e32 v1, v0
	s_ashr_i32 s45, s44, 31
	s_nop 0
	v_permlane32_swap_b32_e32 v0, v1
	v_add_f32_e32 v0, v0, v1
	s_mov_b32 s0, 0x45610000
	v_max_f32_e32 v0, v0, v0
	v_max_f32_e32 v1, v247, v247
	v_max_f32_e32 v4, v248, v248
	v_max_f32_e32 v3, v249, v249
	v_max_f32_e32 v2, v254, v254
	s_nop 0
	v_max_f32_e32 v2, v3, v2
	s_nop 1
	v_max_f32_dpp v0, v0, v0 quad_perm:[1,0,3,2] row_mask:0xf bank_mask:0xf
	v_max_f32_dpp v1, v1, v1 quad_perm:[1,0,3,2] row_mask:0xf bank_mask:0xf
	v_max_f32_dpp v4, v4, v4 quad_perm:[1,0,3,2] row_mask:0xf bank_mask:0xf
	v_max_f32_dpp v2, v2, v2 quad_perm:[1,0,3,2] row_mask:0xf bank_mask:0xf
	v_max_f32_dpp v0, v0, v0 quad_perm:[2,3,0,1] row_mask:0xf bank_mask:0xf
	v_max_f32_dpp v1, v1, v1 quad_perm:[2,3,0,1] row_mask:0xf bank_mask:0xf
	v_max_f32_dpp v4, v4, v4 quad_perm:[2,3,0,1] row_mask:0xf bank_mask:0xf
	v_max_f32_dpp v2, v2, v2 quad_perm:[2,3,0,1] row_mask:0xf bank_mask:0xf
	v_max_f32_dpp v0, v0, v0 row_half_mirror row_mask:0xf bank_mask:0xf
	v_max_f32_dpp v1, v1, v1 row_half_mirror row_mask:0xf bank_mask:0xf
	v_max_f32_dpp v4, v4, v4 row_half_mirror row_mask:0xf bank_mask:0xf
	v_max_f32_dpp v2, v2, v2 row_half_mirror row_mask:0xf bank_mask:0xf
	v_max_f32_dpp v0, v0, v0 row_mirror row_mask:0xf bank_mask:0xf
	v_max_f32_dpp v1, v1, v1 row_mirror row_mask:0xf bank_mask:0xf
	v_max_f32_dpp v4, v4, v4 row_mirror row_mask:0xf bank_mask:0xf
	v_max_f32_dpp v2, v2, v2 row_mirror row_mask:0xf bank_mask:0xf
	v_max_f32_dpp v0, v0, v0 row_bcast:15 row_mask:0xa bank_mask:0xf
	v_max_f32_dpp v1, v1, v1 row_bcast:15 row_mask:0xa bank_mask:0xf
	v_max_f32_dpp v4, v4, v4 row_bcast:15 row_mask:0xa bank_mask:0xf
	v_max_f32_dpp v2, v2, v2 row_bcast:15 row_mask:0xa bank_mask:0xf
	v_max_f32_dpp v0, v0, v0 row_bcast:31 row_mask:0xc bank_mask:0xf
	v_max_f32_dpp v1, v1, v1 row_bcast:31 row_mask:0xc bank_mask:0xf
	v_max_f32_dpp v4, v4, v4 row_bcast:31 row_mask:0xc bank_mask:0xf
	v_max_f32_dpp v2, v2, v2 row_bcast:31 row_mask:0xc bank_mask:0xf
	v_add_f32_e32 v1, v1, v4
	v_add_f32_e32 v1, v2, v1
	v_mul_f32_e32 v0, v0, v1
	v_mul_f32_e32 v0, 0x3f866666, v0
	v_cmp_ge_f32_e32 vcc, s0, v0
	s_nop 1
	v_cndmask_b32_e64 v0, 0, 1, vcc
	s_nop 0
	v_readlane_b32 s0, v0, 63
	s_bitcmp1_b32 s0, 0
	s_cselect_b64 s[44:45], -1, 0
	s_branch .LBB0_559
